# first workgroup of each XCD to reach a grid barrier issues an early L2 write-back so the XCD leader finds the L2 mostly clean, on top of v36
# speedup vs baseline: 1.0178x; 1.0040x over previous
.LBB0_66:
	s_or_b64 exec, exec, s[6:7]
	v_cvt_f32_u32_e32 v5, v3
	s_waitcnt vmcnt(0)
	v_readfirstlane_b32 s4, v4
	v_sub_u32_e32 v4, 0, v3
	v_rcp_iflag_f32_e32 v5, v5
	v_add_u32_e32 v6, s4, v2
	v_mul_f32_e32 v5, 0x4f7ffffe, v5
	v_cvt_u32_f32_e32 v5, v5
	v_mul_lo_u32 v2, v4, v5
	v_mul_hi_u32 v2, v5, v2
	v_add_u32_e32 v2, v5, v2
	v_mul_hi_u32 v2, v6, v2
	v_mul_lo_u32 v4, v2, v3
	v_sub_u32_e32 v4, v6, v4
	v_add_u32_e32 v5, 1, v2
	v_cmp_ge_u32_e32 vcc, v4, v3
	s_nop 1
	v_cndmask_b32_e32 v2, v2, v5, vcc
	v_sub_u32_e32 v5, v4, v3
	v_cndmask_b32_e32 v4, v4, v5, vcc
	v_add_u32_e32 v5, 1, v2
	v_cmp_ge_u32_e32 vcc, v4, v3
	v_add_u32_e32 v4, 1, v6
	s_nop 0
	v_cndmask_b32_e32 v2, v2, v5, vcc
	v_mul_lo_u32 v5, v3, v2
	v_add_u32_e32 v3, v5, v3
	v_cmp_ne_u32_e32 vcc, v4, v3
	s_and_saveexec_b64 s[4:5], vcc
	s_xor_b64 s[4:5], exec, s[4:5]
	s_cbranch_execz .LBB0_80
	v_add_u32_e32 v5, 1, v5
	v_cmp_eq_u32_e32 vcc, v4, v5
	s_cbranch_vccz .Lwb_skip_0
	buffer_wbl2 sc1
.Lwb_skip_0:
	buffer_inv sc1
	s_waitcnt lgkmcnt(0)
	v_mov_b32_e32 v1, 0x2000
	global_load_dword v1, v1, s[2:3] offset:1024 sc1
	s_add_u32 s10, s2, 0x2400
	s_addc_u32 s11, s3, 0
	s_waitcnt vmcnt(0)
	v_cmp_eq_u32_e32 vcc, v1, v2
	s_and_saveexec_b64 s[6:7], vcc
	s_cbranch_execz .LBB0_79
	s_add_u32 s8, s74, 0x4200
	s_addc_u32 s9, s75, 0
	s_mov_b32 s13, 1
	s_mov_b64 s[16:17], 0
	v_mov_b32_e32 v1, 0
	s_branch .LBB0_70

.Lwb_skip_1:
	buffer_inv sc1
	s_waitcnt lgkmcnt(0)
	v_mov_b32_e32 v1, 0x2000
	global_load_dword v1, v1, s[2:3] offset:1024 sc1
	s_add_u32 s10, s2, 0x2400
	s_addc_u32 s11, s3, 0
	s_waitcnt vmcnt(0)
	v_cmp_eq_u32_e32 vcc, v1, v2
	s_and_saveexec_b64 s[6:7], vcc
	s_cbranch_execz .LBB0_192
	s_add_u32 s8, s74, 0x4200
	s_addc_u32 s9, s75, 0
	s_mov_b32 s12, 1
	s_mov_b64 s[16:17], 0
	v_mov_b32_e32 v1, 0
	s_branch .LBB0_183

.Lwb_skip_5:
	buffer_inv sc1
	s_waitcnt lgkmcnt(0)
	v_mov_b32_e32 v1, 0x2000
	global_load_dword v1, v1, s[2:3] offset:1024 sc1
	s_add_u32 s10, s2, 0x2400
	s_addc_u32 s11, s3, 0
	s_waitcnt vmcnt(0)
	v_cmp_eq_u32_e32 vcc, v1, v2
	s_and_saveexec_b64 s[6:7], vcc
	s_cbranch_execz .LBB0_1010
	s_add_u32 s8, s74, 0x4200
	s_addc_u32 s9, s75, 0
	s_mov_b32 s15, 1
	s_mov_b64 s[12:13], 0
	v_mov_b32_e32 v1, 0
	s_branch .LBB0_1001
